# same as previous plus grid-size guard on the stick-breaking work map
# baseline (speedup 1.0000x reference)
; #define LAS __attribute__((address_space(3)))
; #define MFMA32(a, b, c) __builtin_amdgcn_mfma_f32_32x32x16_bf16((a), (b), (c), 0, 0, 0)
; DI void sb_qblock(const bf16_t* __restrict__ PG, bf16_t* __restrict__ Osb, int b, int hh, int qb, LAS unsigned char* vl, int lane) {
;     ...
;   const int i16 = lane & 15, q4l = i16 >> 2, p4 = i16 & 3, gp = (lane >> 4) & 1;
;   LAS unsigned char* trb = vl + (4 * h + q4l) * 320 + (16 * gp + 4 * p4) * 2;
;     ...
;     const int s0 = kb * 32;
;     u32x4 vreg[8];
; #pragma unroll
;     for (int it = 0; it < 8; ++it) { const int idx = it * 64 + lane, row = idx >> 4, ch = idx & 15; vreg[it] = *(const u32x4*)(Vp + (size_t)(s0 + row) * PGW + ch * 8); }
;     f32x16 z;
; #pragma unroll
;     for (int i = 0; i < 16; ++i) z[i] = 0.f;
; #pragma unroll
;     for (int ks = 0; ks < 8; ++ks) z = MFMA32(kf[ks], qf[ks], z);
;     if (kb > 0) {
; #pragma unroll
;       for (int ks = 0; ks < 8; ++ks) kf[ks] = *(const bf16x8*)(Kp + (size_t)(s0 - 32 + r) * PGW + ks * 16 + 8 * h); }
;     const bool diag = (kb == qb);
;     float ls[16], lk[16];
; #pragma unroll
;     for (int i = 0; i < 16; ++i) { const int sl = (i & 3) + 8 * (i >> 2) + 4 * h; const float zz = z[i] * scale;
;       const float l = fminf(zz, 0.f) - __logf(1.0f + __expf(-fabsf(zz)));
;       ls[i] = l; const bool keep = !diag || (sl < r); lk[i] = keep ? (l - zz) : 0.f; }
; DI void sb_phase(const Ctx& cx, const bf16_t* PG, bf16_t* Osb, LAS unsigned char* lds) {
;   const int lane = TID & 63, wid = __builtin_amdgcn_readfirstlane(TID >> 6);
;   LAS unsigned char* vl = lds + wid * 10240;
;   for (int p = BID * 4 + (wid & 3); p < 1024; p += NBLK * 4) {
;     const int bh = p >> 5, i = p & 31;
;     const int qb = (wid < 4) ? i : 63 - i;
;     sb_qblock(PG, Osb, bh >> 3, bh & 7, qb, vl, lane);
.LBB0_897:
	s_and_b64 vcc, exec, s[0:1]
	s_cbranch_vccz .LBB0_936
	s_cmpk_eq_i32 s5, 0x100
	s_cbranch_scc0 .Lsb_nomap
	s_and_b32 s10, s8, 7
	s_lshl_b32 s10, s10, 5
	s_lshr_b32 s11, s8, 3
	s_or_b32 s8, s10, s11
.Lsb_nomap:
	v_readfirstlane_b32 s0, v242
	s_ashr_i32 s1, s0, 6
	s_lshl_b32 s10, s8, 2
	s_and_b32 s0, s1, 3
	s_or_b32 s11, s0, s10
	v_bfe_u32 v218, v242, 5, 1
	s_cmpk_gt_i32 s11, 0x3ff
	v_and_b32_e32 v216, 31, v242
	v_lshrrev_b32_e32 v217, 2, v242
	v_and_b32_e32 v179, 16, v242
	v_lshlrev_b32_e32 v176, 3, v218
	v_lshlrev_b32_e32 v178, 2, v218
	s_cbranch_scc1 .LBB0_908
	v_and_b32_e32 v6, 64, v237
	s_waitcnt lgkmcnt(0)
	v_xor_b32_e32 v5, 32, v237
	v_add_u32_e32 v6, 64, v6
	v_cmp_lt_i32_e32 vcc, v5, v6
	s_mul_i32 s12, s1, 0x2800
	s_add_i32 s12, s12, 0
	v_cndmask_b32_e32 v5, v237, v5, vcc
	v_lshlrev_b32_e32 v219, 2, v5
	v_or_b32_e32 v5, 1, v178
	v_cmp_lt_u32_e64 s[38:39], v5, v216
	v_or_b32_e32 v5, 2, v178
	v_and_b32_e32 v1, 63, v242
	s_cmp_lt_i32 s1, 4
	v_and_or_b32 v2, v217, 3, v178
	v_mov_b32_e32 v3, s12
	s_movk_i32 s1, 0x140
	v_cmp_lt_u32_e64 s[40:41], v5, v216
	v_or_b32_e32 v5, 3, v178
	v_or_b32_e32 v6, 8, v178
	s_cselect_b64 s[88:89], -1, 0
	v_mad_u32_u24 v3, v2, s1, v3
	v_lshlrev_b32_e32 v2, 2, v242
	v_cmp_gt_u32_e64 s[34:35], 32, v1
	v_lshlrev_b32_e32 v1, 4, v242
	v_cmp_lt_u32_e64 s[42:43], v5, v216
	v_or_b32_e32 v5, 10, v178
	v_cmp_lt_u32_e64 s[46:47], v6, v216
	v_or_b32_e32 v6, 16, v178
	s_lshl_b32 s22, s5, 2
	v_readlane_b32 s1, v253, 63
	v_and_or_b32 v2, v2, 12, v179
	v_and_b32_e32 v1, 0xf0, v1
	v_or_b32_e32 v7, 11, v178
	v_or_b32_e32 v8, 9, v178
	v_cmp_lt_u32_e64 s[44:45], v5, v216
	v_or_b32_e32 v5, 18, v178
	v_cmp_lt_u32_e64 s[54:55], v6, v216
	v_or_b32_e32 v6, 24, v178
	s_add_u32 s24, s1, s92
	v_readlane_b32 s1, v254, 0
	v_lshlrev_b32_e32 v4, 1, v2
	v_lshlrev_b32_e32 v2, 3, v242
	v_add_u32_e32 v1, s12, v1
	v_bfe_u32 v220, v242, 4, 2
	v_cmp_lt_u32_e64 s[48:49], v7, v216
	v_cmp_lt_u32_e64 s[50:51], v8, v216
	v_or_b32_e32 v7, 19, v178
	v_or_b32_e32 v8, 17, v178
	v_cmp_lt_u32_e64 s[52:53], v5, v216
	v_or_b32_e32 v5, 26, v178
	v_cmp_lt_u32_e64 s[62:63], v6, v216
	v_lshrrev_b32_e32 v6, 1, v242
	s_addc_u32 s25, s1, s93
	s_lshl_b32 s1, s8, 5
	s_lshl_b32 s12, s0, 3
	v_mul_u32_u24_e32 v0, 0x3000, v216
	v_and_b32_e32 v2, 0x78, v2
	v_cmp_lt_u32_e64 s[56:57], v7, v216
	v_cmp_lt_u32_e64 s[58:59], v8, v216
	v_or_b32_e32 v7, 27, v178
	v_or_b32_e32 v8, 25, v178
	v_cmp_lt_u32_e64 s[60:61], v5, v216
	v_mul_u32_u24_e32 v5, 0x140, v220
	v_and_b32_e32 v208, 16, v6
	s_or_b32 s23, s1, s12
	s_lshl_b32 s1, s8, 4
	s_lshl_b32 s0, s0, 2
	v_or_b32_e32 v177, 0xffffffe0, v242
	v_or_b32_e32 v221, 4, v220
	v_or_b32_e32 v222, 8, v220
	v_or_b32_e32 v223, 12, v220
	v_or_b32_e32 v224, 16, v220
	v_or_b32_e32 v225, 20, v220
	v_or_b32_e32 v226, 24, v220
	v_or_b32_e32 v227, 28, v220
	v_cmp_lt_u32_e64 s[36:37], v178, v216
	v_cmp_lt_u32_e64 s[64:65], v7, v216
	v_cmp_lt_u32_e64 s[66:67], v8, v216
	v_lshl_add_u64 v[180:181], s[24:25], 0, v[208:209]
	s_lshl_b32 s26, s5, 5
	s_or_b32 s27, s1, s0
	s_lshl_b32 s72, s5, 4
	v_lshlrev_b32_e32 v182, 1, v0
	v_lshlrev_b32_e32 v184, 1, v176
	v_lshlrev_b32_e32 v186, 1, v2
	v_lshlrev_b32_e32 v188, 1, v178
	v_add_u32_e32 v228, v1, v5
	v_add_u32_e32 v229, v3, v4
	s_branch .LBB0_901
